# self-canonicalizing v_max pairs after the cross-half permlane removed at 6 row-max sites (bit-identical), on top of the previous version
# baseline (speedup 1.0000x reference)
; __device__ __forceinline__ int v_rd_base(int lane) { return ((lane & 3) << 3) | (((lane >> 2) & 3) << 6) | (((lane >> 4) & 1) << 5) | (((lane >> 5) & 1) << 8); }
; #define DMA_V(t, vo) do { const char* vt_ = (const char*)(Vh + (size_t)(t) * KVBLK * LDK); \
;     _Pragma("unroll") for (int i_ = 0; i_ < 2; ++i_) \
;         __builtin_amdgcn_global_load_lds((const unsigned*)(vt_ + voffV[0] + i_ * 128), (LAS unsigned*)(lds + OFF_VR + (vo) + (wid * 2 + i_) * 1024), 16, 0, 0); } while (0)
; #define LBAR() asm volatile("s_waitcnt vmcnt(0) lgkmcnt(0)\n\ts_barrier" ::: "memory")
; template <int MODE> __device__ __forceinline__ void partialSM(f32x16& p0, f32x16& p1, float& m_reg, float& mn, float& alpha) {
;     float pmax = p0[0];
; #pragma unroll
;     for (int r = 1; r < 16; ++r) pmax = fmaxf(pmax, p0[r]);
; #pragma unroll
;     for (int r = 0; r < 16; ++r) pmax = fmaxf(pmax, p1[r]);
;     { auto rr = __builtin_amdgcn_permlane32_swap(__float_as_uint(pmax), __float_as_uint(pmax), false, false);
;       pmax = fmaxf(__uint_as_float(rr[0]), __uint_as_float(rr[1])); }
;     if (__builtin_expect(__all(pmax - m_reg <= Cst<MODE>::THRS), 1)) { mn = m_reg; alpha = 1.f; }
; template <int MODE, bool STORE = true> ...
;     ...
;     unsigned voffV[2], voffK[2];
; #pragma unroll
;     for (int i = 0; i < 2; ++i) {
;         const int c = wid * 2 + i, ob = c * 1024 + lane * 16;
;         { const int sub = ob >> 9, within = ob & 511, kk = (sub >> 2) * 8 + (within >> 6), k = (kk & ~0xC) | ((kk & 4) << 1) | ((kk & 8) >> 1), col = (sub & 3) * 32 + ((within & 63) >> 1);
;           voffV[i] = (unsigned)(k * LDK + col) * 2u; }
;         { const int row = 4 * c + (lane >> 4), g = lane & 15; voffK[i] = (unsigned)(row * LDK + ((g ^ (row & 15)) * 8)) * 2u; }
;     }
;     const int vb0 = (int)(unsigned)(uintptr_t)lds + v_rd_base(lane);
;     ...
;     f32x16 pA0, pA1, pB0, pB1; float mnA, alA, alB; bf16x8 pa0, pa1, pa2, pa3; const int NT = seq / KVBLK;
;     const bool g2 = wid >= 4;
;     if (g2) __builtin_amdgcn_s_setprio(1);
;     int k_cur = 0, v_pp = SHM_V, v_p = 2 * SHM_V, v_c = 0;
;     DMA_K(0, 0); DMA_K(1, 1); DMA_V(0, 0); LBAR();
;     qkt<MODE>(pA0, pA1, KB(0), KRB(0), qr, r32, hi, comp); partialSM<MODE>(pA0, pA1, m_reg, mnA, alA);
.LBB0_536:
	s_mulk_i32 s31, 0x1800
	s_add_u32 s1, s43, s31
	s_addc_u32 s4, s70, 0
	s_add_u32 s64, s1, s0
	s_addc_u32 s65, s4, 0
	s_add_u32 s46, s64, 0x1000
	s_addc_u32 s47, s65, 0
	s_lshl_b32 s0, s17, 3
	v_lshrrev_b32_e32 v1, 2, v0
	v_bfe_u32 v34, v0, 2, 2
	s_and_b32 s66, s0, 0x7ffffff0
	v_and_b32_e32 v35, 4, v1
	s_lshl_b32 s1, s17, 3
	v_and_b32_e32 v149, 63, v0
	s_and_b32 s67, s1, 8
	v_or3_b32 v1, v35, v34, s66
	v_lshlrev_b32_e32 v36, 3, v149
	v_or_b32_e32 v1, s67, v1
	v_lshrrev_b32_e32 v32, 4, v149
	v_and_b32_e32 v37, 32, v0
	v_and_b32_e32 v38, 24, v36
	v_mul_lo_u32 v1, v1, s71
	v_or_b32_e32 v2, s0, v32
	v_bitop3_b32 v3, s0, v0, v32 bitop3:0x36
	v_or3_b32 v1, v1, v37, v38
	v_lshlrev_b32_e32 v3, 3, v3
	v_bitop3_b32 v0, v2, v0, 4 bitop3:0x36
	v_lshlrev_b32_e32 v150, 1, v1
	v_mul_lo_u32 v1, v2, s71
	v_and_b32_e32 v33, 0x78, v3
	v_lshlrev_b32_e32 v0, 3, v0
	v_or_b32_e32 v3, v33, v1
	v_and_b32_e32 v39, 0x78, v0
	s_lshl_b32 s28, s17, 11
	v_lshlrev_b32_e32 v146, 1, v3
	v_or_b32_e32 v0, v1, v39
	s_add_i32 s89, s28, 0
	v_lshl_add_u32 v152, v0, 1, v164
	s_add_i32 s85, s89, 0xc000
	v_lshl_add_u64 v[0:1], s[64:65], 0, v[146:147]
	v_lshl_add_u64 v[0:1], v[0:1], 0, s[20:21]
	s_mov_b32 m0, s85
	v_mov_b32_e32 v153, v147
	s_add_i32 s84, s89, 0xc400
	global_load_lds_dwordx4 v[0:1], off
	v_lshl_add_u64 v[0:1], s[64:65], 0, v[152:153]
	s_add_u32 s0, s64, 0x60800
	v_lshl_add_u64 v[0:1], v[0:1], 0, s[20:21]
	s_mov_b32 m0, s84
	s_addc_u32 s1, s65, 0
	s_add_i32 s90, s89, 0x10000
	global_load_lds_dwordx4 v[0:1], off
	s_mov_b32 m0, s90
	s_add_i32 s91, s89, 0x10400
	global_load_lds_dwordx4 v146, s[0:1]
	s_mov_b32 m0, s91
	v_mov_b32_e32 v151, v147
	global_load_lds_dwordx4 v152, s[0:1]
	v_lshl_add_u64 v[0:1], s[46:47], 0, v[150:151]
	s_mov_b32 m0, s89
	v_lshl_add_u64 v[0:1], v[0:1], 0, s[22:23]
	global_load_lds_dwordx4 v150, s[46:47]
	s_add_i32 m0, s89, 0x400
	s_lshl_b32 s0, s18, 7
	global_load_lds_dwordx4 v[0:1], off
	v_lshlrev_b32_e32 v0, 4, v167
	v_lshlrev_b32_e32 v40, 8, v167
	v_and_b32_e32 v41, 0xf0, v0
	v_add_u32_e32 v46, 0, v40
	v_bitop3_b32 v171, s0, v41, v148 bitop3:0x36
	s_waitcnt vmcnt(0) lgkmcnt(0)
	s_barrier
	v_add_u32_e32 v172, v46, v171
	ds_read_b128 v[0:3], v172 offset:49152
	v_or_b32_e32 v47, s0, v148
	v_bitop3_b32 v173, v47, v41, 32 bitop3:0x36
	v_add_u32_e32 v174, v46, v173
	ds_read_b128 v[42:45], v174 offset:49152
	s_waitcnt vmcnt(0) lgkmcnt(0)
	v_mfma_f32_32x32x16_bf16 v[16:31], v[0:3], v[140:143], 0
	ds_read_b128 v[0:3], v172 offset:57344
	v_bitop3_b32 v175, v47, v41, 64 bitop3:0x36
	v_add_u32_e32 v176, v46, v175
	s_movk_i32 s0, 0x60
	v_bitop3_b32 v177, v47, v41, s0 bitop3:0x36
	v_add_u32_e32 v178, v46, v177
	s_mov_b64 s[4:5], -1
	v_mfma_f32_32x32x16_bf16 v[16:31], v[42:45], v[136:139], v[16:31]
	ds_read_b128 v[42:45], v174 offset:57344
	s_waitcnt lgkmcnt(1)
	v_mfma_f32_32x32x16_bf16 v[0:15], v[0:3], v[140:143], 0
	s_waitcnt lgkmcnt(0)
	v_mfma_f32_32x32x16_bf16 v[0:15], v[42:45], v[136:139], v[0:15]
	ds_read_b128 v[42:45], v176 offset:49152
	s_waitcnt lgkmcnt(0)
	v_mfma_f32_32x32x16_bf16 v[16:31], v[42:45], v[132:135], v[16:31]
	ds_read_b128 v[42:45], v176 offset:57344
	s_waitcnt lgkmcnt(0)
	v_mfma_f32_32x32x16_bf16 v[0:15], v[42:45], v[132:135], v[0:15]
	ds_read_b128 v[42:45], v178 offset:49152
	s_waitcnt lgkmcnt(0)
	v_mfma_f32_32x32x16_bf16 v[16:31], v[42:45], v[128:131], v[16:31]
	ds_read_b128 v[42:45], v178 offset:57344
	s_waitcnt lgkmcnt(0)
	v_mfma_f32_32x32x16_bf16 v[0:15], v[42:45], v[128:131], v[0:15]
	s_nop 8
	v_max_f32_e32 v41, v17, v17
	v_max_f32_e32 v42, v16, v16
	v_max_f32_e32 v41, v42, v41
	v_max3_f32 v41, v41, v18, v19
	v_max3_f32 v41, v41, v20, v21
	v_max3_f32 v41, v41, v22, v23
	v_max3_f32 v41, v41, v24, v25
	v_max3_f32 v41, v41, v26, v27
	v_max3_f32 v41, v41, v28, v29
	v_max3_f32 v41, v41, v30, v31
	v_max3_f32 v41, v41, v0, v1
	v_max3_f32 v41, v41, v2, v3
	v_max3_f32 v41, v41, v4, v5
	v_max3_f32 v41, v41, v6, v7
	v_max3_f32 v41, v41, v8, v9
	v_max3_f32 v41, v41, v10, v11
	v_max3_f32 v41, v41, v12, v13
	v_max3_f32 v41, v41, v14, v15
	v_mov_b32_e32 v42, v41
	s_nop 1
	v_permlane32_swap_b32_e32 v41, v42
	v_max_f32_e32 v41, v41, v42
	v_add_f32_e32 v42, 0x7149f2ca, v41
	v_cmp_ge_f32_e32 vcc, s72, v42
	s_cmp_eq_u64 vcc, exec
	s_cselect_b64 s[0:1], -1, 0
	s_and_b64 vcc, exec, s[48:49]
	s_cbranch_vccz .LBB0_538
	s_waitcnt vmcnt(0) lgkmcnt(0)
	s_barrier
	s_mov_b64 s[4:5], 0

; #define SBAR() __builtin_amdgcn_sched_barrier(0)
; #define LW(n) asm volatile("s_waitcnt lgkmcnt(" #n ")" ::: "memory")
; template <int MODE, bool PF> __device__ __forceinline__ void pv_partial(f32x16* o, int vb, bf16x8 pa0, bf16x8 pa1, bf16x8 pa2, bf16x8 pa3, f32x16& p0, f32x16& p1, float& m_reg, float& alpha) {
;     VFrag fa, fb;
;     v_frag_read<0>(fa, vb);
;     if constexpr (PF) { v_frag_read<1>(fb, vb); LW(8); } else LW(0);
;     SBAR();
;     pv_mma(o[0], fa, pa0, pa1, pa2, pa3);
;     float pm0 = p0[0];
; #pragma unroll
;     for (int r = 1; r < 16; ++r) pm0 = fmaxf(pm0, p0[r]);
;     if constexpr (PF) { v_frag_read<2>(fa, vb); LW(8); } else { v_frag_read<1>(fb, vb); LW(0); }
;     SBAR();
;     pv_mma(o[1], fb, pa0, pa1, pa2, pa3);
;     float pmax = pm0;
; #pragma unroll
;     for (int r = 0; r < 16; ++r) pmax = fmaxf(pmax, p1[r]);
;     { auto rr = __builtin_amdgcn_permlane32_swap(__float_as_uint(pmax), __float_as_uint(pmax), false, false);
;       pmax = fmaxf(__uint_as_float(rr[0]), __uint_as_float(rr[1])); }
;     const float mn = (pmax - m_reg > Cst<MODE>::THRS) ? fmaxf(m_reg, pmax) : m_reg;
;     alpha = __builtin_amdgcn_exp2f(m_reg - mn); m_reg = mn;
;     const f32x16 mnv = {mn, mn, mn, mn, mn, mn, mn, mn, mn, mn, mn, mn, mn, mn, mn, mn};
;     if constexpr (PF) { v_frag_read<3>(fb, vb); LW(8); } else { v_frag_read<2>(fa, vb); LW(0); }
;     SBAR();
;     pv_mma(o[2], fa, pa0, pa1, pa2, pa3);
;     p0 = p0 - mnv; p1 = p1 - mnv;
; #pragma unroll
;     for (int r = 0; r < 8; ++r) p0[r] = __builtin_amdgcn_exp2f(p0[r]);
;     if constexpr (PF) { LW(0); } else { v_frag_read<3>(fb, vb); LW(0); }
;     SBAR();
;     pv_mma(o[3], fb, pa0, pa1, pa2, pa3);
; #pragma unroll
;     for (int r = 8; r < 16; ++r) p0[r] = __builtin_amdgcn_exp2f(p0[r]);
;     asm volatile("" : "+v"(p0), "+v"(p1));
; }
.LBB0_575:
	v_add_u32_e32 v146, s92, v170
	ds_read_b64_tr_b16 v[64:65], v146 offset:0
	ds_read_b64_tr_b16 v[66:67], v146 offset:0x800
	ds_read_b64_tr_b16 v[68:69], v146 offset:0x1000
	ds_read_b64_tr_b16 v[70:71], v146 offset:0x1800
	ds_read_b64_tr_b16 v[80:81], v146 offset:0x2000
	ds_read_b64_tr_b16 v[82:83], v146 offset:0x2800
	ds_read_b64_tr_b16 v[84:85], v146 offset:0x3000
	ds_read_b64_tr_b16 v[86:87], v146 offset:0x3800
	ds_read_b64_tr_b16 v[88:89], v146 offset:0x200
	ds_read_b64_tr_b16 v[90:91], v146 offset:0xa00
	ds_read_b64_tr_b16 v[92:93], v146 offset:0x1200
	ds_read_b64_tr_b16 v[94:95], v146 offset:0x1a00
	ds_read_b64_tr_b16 v[138:139], v146 offset:0x2200
	ds_read_b64_tr_b16 v[140:141], v146 offset:0x2a00
	ds_read_b64_tr_b16 v[152:153], v146 offset:0x3200
	ds_read_b64_tr_b16 v[154:155], v146 offset:0x3a00
	s_waitcnt lgkmcnt(8)
	s_nop 0
	v_mfma_f32_32x32x16_bf16 v[16:31], v[132:135], v[64:67], v[16:31]
	v_max_f32_e32 v64, v96, v97
	v_max3_f32 v64, v64, v98, v99
	v_max3_f32 v64, v64, v100, v101
	v_max3_f32 v64, v64, v102, v103
	v_max3_f32 v64, v64, v104, v105
	v_mfma_f32_32x32x16_bf16 v[16:31], v[72:75], v[68:71], v[16:31]
	v_max3_f32 v64, v64, v106, v107
	v_max3_f32 v66, v64, v108, v109
	ds_read_b64_tr_b16 v[64:65], v146 offset:0x400
	v_max3_f32 v142, v66, v110, v111
	ds_read_b64_tr_b16 v[66:67], v146 offset:0xc00
	ds_read_b64_tr_b16 v[68:69], v146 offset:0x1400
	ds_read_b64_tr_b16 v[70:71], v146 offset:0x1c00
	v_mfma_f32_32x32x16_bf16 v[16:31], v[76:79], v[80:83], v[16:31]
	ds_read_b64_tr_b16 v[80:81], v146 offset:0x2400
	ds_read_b64_tr_b16 v[82:83], v146 offset:0x2c00
	ds_read_b64_tr_b16 v[156:157], v146 offset:0x3400
	ds_read_b64_tr_b16 v[158:159], v146 offset:0x3c00
	s_waitcnt lgkmcnt(8)
	v_mfma_f32_32x32x16_bf16 v[16:31], v[128:131], v[84:87], v[16:31]
	v_mfma_f32_32x32x16_bf16 v[48:63], v[132:135], v[88:91], v[48:63]
	v_max3_f32 v84, v142, v112, v113
	v_max3_f32 v84, v84, v114, v115
	v_max3_f32 v84, v84, v116, v117
	v_max3_f32 v84, v84, v118, v119
	v_max3_f32 v84, v84, v120, v121
	v_max3_f32 v84, v84, v122, v123
	v_max3_f32 v84, v84, v124, v125
	v_mfma_f32_32x32x16_bf16 v[48:63], v[72:75], v[92:95], v[48:63]
	v_max3_f32 v84, v84, v126, v127
	v_mov_b32_e32 v85, v84
	s_nop 1
	v_permlane32_swap_b32_e32 v84, v85
	v_max_f32_e32 v84, v84, v85
	v_mfma_f32_32x32x16_bf16 v[48:63], v[76:79], v[138:141], v[48:63]
	ds_read_b64_tr_b16 v[140:141], v146 offset:0x600
	ds_read_b64_tr_b16 v[142:143], v146 offset:0xe00
	ds_read_b64_tr_b16 v[170:171], v146 offset:0x1600
	v_sub_f32_e32 v85, v84, v186
	v_max_f32_e32 v86, v186, v186
	ds_read_b64_tr_b16 v[172:173], v146 offset:0x1e00
	v_max_f32_e32 v84, v86, v84
	v_mfma_f32_32x32x16_bf16 v[48:63], v[128:131], v[152:155], v[48:63]
	v_cmp_lt_f32_e32 vcc, s72, v85
	ds_read_b64_tr_b16 v[174:175], v146 offset:0x2600
	ds_read_b64_tr_b16 v[176:177], v146 offset:0x2e00
	ds_read_b64_tr_b16 v[152:153], v146 offset:0x3600
	ds_read_b64_tr_b16 v[154:155], v146 offset:0x3e00
	s_waitcnt lgkmcnt(8)
	s_nop 1
	v_cndmask_b32_e32 v160, v186, v84, vcc
	v_sub_f32_e32 v84, v186, v160
	v_exp_f32_e32 v138, v84
	v_mfma_f32_32x32x16_bf16 v[32:47], v[132:135], v[64:67], v[32:47]
	v_sub_f32_e32 v103, v103, v160
	v_sub_f32_e32 v102, v102, v160
	v_sub_f32_e32 v101, v101, v160
	v_sub_f32_e32 v100, v100, v160
	v_sub_f32_e32 v67, v99, v160
	v_sub_f32_e32 v66, v98, v160
	v_sub_f32_e32 v65, v97, v160
	v_mfma_f32_32x32x16_bf16 v[32:47], v[72:75], v[68:71], v[32:47]
	v_sub_f32_e32 v64, v96, v160
	v_exp_f32_e32 v64, v64
	v_exp_f32_e32 v65, v65
	v_exp_f32_e32 v66, v66
	v_exp_f32_e32 v67, v67
	v_exp_f32_e32 v68, v100
	v_exp_f32_e32 v69, v101
	v_mfma_f32_32x32x16_bf16 v[32:47], v[76:79], v[80:83], v[32:47]
	v_exp_f32_e32 v70, v102
	v_exp_f32_e32 v71, v103
	s_waitcnt lgkmcnt(0)
	v_sub_f32_e32 v95, v127, v160
	v_sub_f32_e32 v94, v126, v160
	v_sub_f32_e32 v93, v125, v160
	v_sub_f32_e32 v92, v124, v160
	v_mfma_f32_32x32x16_bf16 v[32:47], v[128:131], v[156:159], v[32:47]
	v_sub_f32_e32 v91, v123, v160
	v_sub_f32_e32 v90, v122, v160
	v_sub_f32_e32 v89, v121, v160
	v_sub_f32_e32 v88, v120, v160
	v_sub_f32_e32 v87, v119, v160
	v_sub_f32_e32 v86, v118, v160
	v_sub_f32_e32 v85, v117, v160
	v_sub_f32_e32 v84, v116, v160
	v_sub_f32_e32 v83, v115, v160
	v_sub_f32_e32 v82, v114, v160
	v_sub_f32_e32 v81, v113, v160
	v_sub_f32_e32 v80, v112, v160
	v_sub_f32_e32 v111, v111, v160
	v_sub_f32_e32 v110, v110, v160
	v_sub_f32_e32 v109, v109, v160
	v_sub_f32_e32 v108, v108, v160
	v_sub_f32_e32 v107, v107, v160
	v_sub_f32_e32 v106, v106, v160
	v_sub_f32_e32 v105, v105, v160
	v_sub_f32_e32 v104, v104, v160
	v_mfma_f32_32x32x16_bf16 v[0:15], v[132:135], v[140:143], v[0:15]
	v_cmp_gt_f32_e32 vcc, 1.0, v138
	v_mfma_f32_32x32x16_bf16 v[0:15], v[72:75], v[170:173], v[0:15]
	v_exp_f32_e32 v72, v104
	v_exp_f32_e32 v73, v105
	v_exp_f32_e32 v74, v106
	v_exp_f32_e32 v75, v107
	v_mfma_f32_32x32x16_bf16 v[0:15], v[76:79], v[174:177], v[0:15]
	v_exp_f32_e32 v76, v108
	v_exp_f32_e32 v77, v109
	v_exp_f32_e32 v78, v110
	v_exp_f32_e32 v79, v111
	v_mfma_f32_32x32x16_bf16 v[0:15], v[128:131], v[152:155], v[0:15]
	s_cbranch_vccz .LBB0_579
	s_and_saveexec_b64 s[2:3], s[0:1]
	ds_write_b32 v168, v138 offset:128
	s_or_b64 exec, exec, s[2:3]
	s_waitcnt lgkmcnt(0)
	v_add_u32_e32 v108, s19, v148
	ds_read_b128 v[96:99], v108 offset:224
	ds_read_b128 v[100:103], v108 offset:192
	ds_read_b128 v[104:107], v108 offset:160
	ds_read_b128 v[108:111], v108 offset:128
	s_waitcnt lgkmcnt(0)
	v_pk_mul_f32 v[28:29], v[28:29], v[96:97]
	v_pk_mul_f32 v[24:25], v[24:25], v[100:101]
	v_pk_mul_f32 v[20:21], v[20:21], v[104:105]
	v_pk_mul_f32 v[30:31], v[30:31], v[98:99]
	v_pk_mul_f32 v[26:27], v[26:27], v[102:103]
	v_pk_mul_f32 v[22:23], v[22:23], v[106:107]
	v_pk_mul_f32 v[18:19], v[18:19], v[110:111]
	v_pk_mul_f32 v[16:17], v[16:17], v[108:109]
	v_pk_mul_f32 v[60:61], v[60:61], v[96:97]
	v_pk_mul_f32 v[56:57], v[56:57], v[100:101]
	v_pk_mul_f32 v[52:53], v[52:53], v[104:105]
	v_pk_mul_f32 v[62:63], v[62:63], v[98:99]
	v_pk_mul_f32 v[58:59], v[58:59], v[102:103]
	v_pk_mul_f32 v[54:55], v[54:55], v[106:107]
	v_pk_mul_f32 v[50:51], v[50:51], v[110:111]
	v_pk_mul_f32 v[48:49], v[48:49], v[108:109]
	v_pk_mul_f32 v[44:45], v[44:45], v[96:97]
	v_pk_mul_f32 v[40:41], v[40:41], v[100:101]
	v_pk_mul_f32 v[36:37], v[36:37], v[104:105]
	v_pk_mul_f32 v[46:47], v[46:47], v[98:99]
	v_pk_mul_f32 v[42:43], v[42:43], v[102:103]
	v_pk_mul_f32 v[38:39], v[38:39], v[106:107]
	v_pk_mul_f32 v[34:35], v[34:35], v[110:111]
	v_pk_mul_f32 v[32:33], v[32:33], v[108:109]
	v_pk_mul_f32 v[12:13], v[12:13], v[96:97]
	v_pk_mul_f32 v[8:9], v[8:9], v[100:101]
	v_pk_mul_f32 v[4:5], v[4:5], v[104:105]
	v_pk_mul_f32 v[14:15], v[14:15], v[98:99]
	v_pk_mul_f32 v[10:11], v[10:11], v[102:103]
	v_pk_mul_f32 v[6:7], v[6:7], v[106:107]
	v_pk_mul_f32 v[2:3], v[2:3], v[110:111]
	v_pk_mul_f32 v[0:1], v[0:1], v[108:109]

; __device__ __forceinline__ int v_rd_base(int lane) { return ((lane & 3) << 3) | (((lane >> 2) & 3) << 6) | (((lane >> 4) & 1) << 5) | (((lane >> 5) & 1) << 8); }
; #define DMA_V(t, vo) do { const char* vt_ = (const char*)(Vh + (size_t)(t) * KVBLK * LDK); \
;     _Pragma("unroll") for (int i_ = 0; i_ < 2; ++i_) \
;         __builtin_amdgcn_global_load_lds((const unsigned*)(vt_ + voffV[0] + i_ * 128), (LAS unsigned*)(lds + OFF_VR + (vo) + (wid * 2 + i_) * 1024), 16, 0, 0); } while (0)
; #define LBAR() asm volatile("s_waitcnt vmcnt(0) lgkmcnt(0)\n\ts_barrier" ::: "memory")
; template <int MODE, bool STORE = true> ...
;     ...
;     unsigned voffV[2], voffK[2];
; #pragma unroll
;     for (int i = 0; i < 2; ++i) {
;         const int c = wid * 2 + i, ob = c * 1024 + lane * 16;
;         { const int sub = ob >> 9, within = ob & 511, kk = (sub >> 2) * 8 + (within >> 6), k = (kk & ~0xC) | ((kk & 4) << 1) | ((kk & 8) >> 1), col = (sub & 3) * 32 + ((within & 63) >> 1);
;           voffV[i] = (unsigned)(k * LDK + col) * 2u; }
;         { const int row = 4 * c + (lane >> 4), g = lane & 15; voffK[i] = (unsigned)(row * LDK + ((g ^ (row & 15)) * 8)) * 2u; }
;     }
;     const int vb0 = (int)(unsigned)(uintptr_t)lds + v_rd_base(lane);
;     ...
;     f32x16 pA0, pA1, pB0, pB1; float mnA, alA, alB; bf16x8 pa0, pa1, pa2, pa3; const int NT = seq / KVBLK;
;     const bool g2 = wid >= 4;
;     if (g2) __builtin_amdgcn_s_setprio(1);
;     int k_cur = 0, v_pp = SHM_V, v_p = 2 * SHM_V, v_c = 0;
;     DMA_K(0, 0); DMA_K(1, 1); DMA_V(0, 0); LBAR();
.LBB0_595:
	s_lshl_b32 s75, s0, 12
	s_add_u32 s1, s29, s75
	s_addc_u32 s4, s30, 0
	s_lshl_b32 s5, s49, 9
	s_add_u32 s64, s1, s5
	s_addc_u32 s65, s4, 0
	s_lshl_b32 s74, s0, 7
	v_and_b32_e32 v38, 63, v36
	s_add_u32 s72, s19, s74
	s_addc_u32 s73, s28, 0
	v_lshlrev_b32_e32 v43, 3, v38
	s_lshl_b32 s0, s16, 3
	v_lshrrev_b32_e32 v0, 2, v36
	v_bfe_u32 v41, v36, 2, 2
	s_and_b32 s83, s0, 0xffff0
	v_and_b32_e32 v42, 4, v0
	s_lshl_b32 s1, s16, 3
	v_and_b32_e32 v45, 24, v43
	s_and_b32 s92, s1, 8
	v_or3_b32 v0, v42, v41, s83
	v_and_or_b32 v1, v36, 32, v45
	v_lshrrev_b32_e32 v37, 4, v38
	v_or_b32_e32 v0, s92, v0
	v_or_b32_e32 v2, s0, v37
	v_lshlrev_b32_e32 v1, 1, v1
	v_lshl_or_b32 v180, v0, 12, v1
	v_bitop3_b32 v0, s0, v36, v37 bitop3:0x36
	v_bitop3_b32 v1, v2, v36, 4 bitop3:0x36
	v_lshlrev_b32_e32 v0, 4, v0
	v_lshlrev_b32_e32 v1, 4, v1
	s_lshl_b32 s80, s16, 11
	v_and_b32_e32 v39, 0xf0, v0
	v_or_b32_e32 v0, 4, v2
	v_and_b32_e32 v40, 0xf0, v1
	s_add_i32 s84, s80, 0
	v_lshrrev_b32_e32 v44, 3, v38
	v_lshl_or_b32 v184, v0, 12, v40
	s_add_i32 s69, s84, 0xc000
	v_or_b32_e32 v0, s0, v44
	v_lshl_or_b32 v182, v2, 12, v39
	s_mov_b32 m0, s69
	s_add_i32 s20, s84, 0xc400
	v_lshrrev_b32_e32 v1, 1, v0
	global_load_lds_dwordx4 v182, s[64:65]
	s_mov_b32 m0, s20
	v_xor_b32_e32 v1, v1, v36
	s_lshl_b32 s93, s16, 10
	global_load_lds_dwordx4 v184, s[64:65]
	v_lshlrev_b32_e32 v1, 4, v1
	s_add_i32 m0, s35, s93
	v_and_b32_e32 v46, 0x70, v1
	s_add_u32 s0, s64, 0x40000
	v_lshl_or_b32 v176, v0, 7, v46
	s_addc_u32 s1, s65, 0
	s_add_i32 s89, s84, 0x10000
	global_load_lds_dwordx4 v176, s[72:73]
	s_mov_b32 m0, s89
	s_add_i32 s90, s84, 0x10400
	global_load_lds_dwordx4 v182, s[0:1]
	s_mov_b32 m0, s90
	s_add_i32 s85, s93, 0
	v_lshl_add_u64 v[32:33], s[72:73], 0, v[176:177]
	global_load_lds_dwordx4 v184, s[0:1]
	s_mov_b64 s[0:1], 0x2000
	s_add_i32 s91, s85, 0x16000
	v_mov_b32_e32 v181, v177
	v_lshl_add_u64 v[0:1], v[32:33], 0, s[0:1]
	s_mov_b32 m0, s91
	v_lshl_add_u64 v[34:35], s[64:65], 0, v[180:181]
	global_load_lds_dwordx4 v[0:1], off
	v_lshl_add_u64 v[0:1], v[34:35], 0, s[22:23]
	s_mov_b32 m0, s84
	v_lshlrev_b32_e32 v47, 8, v254
	global_load_lds_dwordx4 v[0:1], off
	v_lshl_add_u64 v[0:1], v[34:35], 0, s[24:25]
	s_add_i32 m0, s84, 0x400
	s_movk_i32 s0, 0xf0
	global_load_lds_dwordx4 v[0:1], off
	v_lshlrev_b32_e32 v0, 4, v254
	v_add_u32_e32 v57, 0, v47
	v_bitop3_b32 v204, v178, v0, s0 bitop3:0x78
	s_waitcnt vmcnt(0) lgkmcnt(0)
	s_barrier
; #define LAS __attribute__((address_space(3)))
; template <int MODE> __device__ __forceinline__ void partialSM(f32x16& p0, f32x16& p1, float& m_reg, float& mn, float& alpha) {
;     float pmax = p0[0];
; #pragma unroll
;     for (int r = 1; r < 16; ++r) pmax = fmaxf(pmax, p0[r]);
; #pragma unroll
;     for (int r = 0; r < 16; ++r) pmax = fmaxf(pmax, p1[r]);
;     { auto rr = __builtin_amdgcn_permlane32_swap(__float_as_uint(pmax), __float_as_uint(pmax), false, false);
;       pmax = fmaxf(__uint_as_float(rr[0]), __uint_as_float(rr[1])); }
;     if (__builtin_expect(__all(pmax - m_reg <= Cst<MODE>::THRS), 1)) { mn = m_reg; alpha = 1.f; }
; template <int MODE> __device__ __forceinline__ void qkt(f32x16& p0, f32x16& p1, const LAS unsigned char* Kt, const LAS unsigned char* Krt, const bf16x8* qr, int r32, int hi, int comp) {
;     p0 = f32x16{}; p1 = f32x16{};
;     constexpr int NDN = MODE ? 8 : 4;
; #pragma unroll
;     for (int d0 = 0; d0 < NDN; ++d0) { const int cb = ((MODE ? 0 : comp * 64) + d0 * 16 + hi * 8) * 2;
;         const bf16x8 b0 = *(const LAS bf16x8*)(Kt + KSWZ(r32, cb));
;         const bf16x8 b1 = *(const LAS bf16x8*)(Kt + KSWZ(32 + r32, cb));
;         p0 = __builtin_amdgcn_mfma_f32_32x32x16_bf16(b0, qr[d0], p0, 0, 0, 0);
;         p1 = __builtin_amdgcn_mfma_f32_32x32x16_bf16(b1, qr[d0], p1, 0, 0, 0); }
;     if constexpr (MODE == 1) {
; #pragma unroll
;         for (int d0 = 0; d0 < 4; ++d0) { const int cb = (d0 * 16 + hi * 8) * 2;
;             const bf16x8 b0 = *(const LAS bf16x8*)(Krt + KRSWZ(r32, cb));
;             const bf16x8 b1 = *(const LAS bf16x8*)(Krt + KRSWZ(32 + r32, cb));
;             p0 = __builtin_amdgcn_mfma_f32_32x32x16_bf16(b0, qr[8 + d0], p0, 0, 0, 0);
;             p1 = __builtin_amdgcn_mfma_f32_32x32x16_bf16(b1, qr[8 + d0], p1, 0, 0, 0); }
;     }
; }
	v_add_u32_e32 v205, v57, v204
	v_and_b32_e32 v56, 0xf0, v0
	ds_read_b128 v[0:3], v205 offset:49152
	ds_read_b128 v[4:7], v205 offset:57344
	s_waitcnt vmcnt(0) lgkmcnt(0)
	v_mfma_f32_32x32x16_bf16 v[16:31], v[0:3], v[172:175], 0
	v_bitop3_b32 v206, v178, v56, 32 bitop3:0x36
	v_add_u32_e32 v207, v57, v206
	ds_read_b128 v[48:51], v207 offset:49152
	ds_read_b128 v[52:55], v207 offset:57344
	v_bitop3_b32 v208, v178, v56, 64 bitop3:0x36
	v_add_u32_e32 v209, v57, v208
	v_bitop3_b32 v210, v178, v56, s76 bitop3:0x36
	v_add_u32_e32 v211, v57, v210
	v_mfma_f32_32x32x16_bf16 v[0:15], v[4:7], v[172:175], 0
	s_movk_i32 s0, 0x80
	v_bitop3_b32 v212, v178, v56, s0 bitop3:0x36
	v_add_u32_e32 v213, v57, v212
	s_movk_i32 s0, 0xa0
	v_bitop3_b32 v214, v178, v56, s0 bitop3:0x36
	v_add_u32_e32 v215, v57, v214
	v_bitop3_b32 v216, v178, v56, s77 bitop3:0x36
	s_waitcnt lgkmcnt(1)
	v_mfma_f32_32x32x16_bf16 v[16:31], v[48:51], v[168:171], v[16:31]
	v_add_u32_e32 v217, v57, v216
	s_movk_i32 s0, 0xe0
	v_bitop3_b32 v218, v178, v56, s0 bitop3:0x36
	v_add_u32_e32 v219, v57, v218
	s_movk_i32 s0, 0x70
	s_mov_b64 s[4:5], -1
	s_waitcnt lgkmcnt(0)
	v_mfma_f32_32x32x16_bf16 v[0:15], v[52:55], v[168:171], v[0:15]
	ds_read_b128 v[48:51], v209 offset:49152
	ds_read_b128 v[52:55], v209 offset:57344
	s_waitcnt lgkmcnt(1)
	v_mfma_f32_32x32x16_bf16 v[16:31], v[48:51], v[164:167], v[16:31]
	s_waitcnt lgkmcnt(0)
	v_mfma_f32_32x32x16_bf16 v[0:15], v[52:55], v[164:167], v[0:15]
	ds_read_b128 v[48:51], v211 offset:49152
	ds_read_b128 v[52:55], v211 offset:57344
	s_waitcnt lgkmcnt(1)
	v_mfma_f32_32x32x16_bf16 v[16:31], v[48:51], v[160:163], v[16:31]
	s_waitcnt lgkmcnt(0)
	v_mfma_f32_32x32x16_bf16 v[0:15], v[52:55], v[160:163], v[0:15]
	ds_read_b128 v[48:51], v213 offset:49152
	ds_read_b128 v[52:55], v213 offset:57344
	s_waitcnt lgkmcnt(1)
	v_mfma_f32_32x32x16_bf16 v[16:31], v[48:51], v[156:159], v[16:31]
	s_waitcnt lgkmcnt(0)
	v_mfma_f32_32x32x16_bf16 v[0:15], v[52:55], v[156:159], v[0:15]
	ds_read_b128 v[48:51], v215 offset:49152
	ds_read_b128 v[52:55], v215 offset:57344
	s_waitcnt lgkmcnt(1)
	v_mfma_f32_32x32x16_bf16 v[16:31], v[48:51], v[152:155], v[16:31]
	s_waitcnt lgkmcnt(0)
	v_mfma_f32_32x32x16_bf16 v[0:15], v[52:55], v[152:155], v[0:15]
	ds_read_b128 v[48:51], v217 offset:49152
	ds_read_b128 v[52:55], v217 offset:57344
	s_waitcnt lgkmcnt(1)
	v_mfma_f32_32x32x16_bf16 v[16:31], v[48:51], v[148:151], v[16:31]
	s_waitcnt lgkmcnt(0)
	v_mfma_f32_32x32x16_bf16 v[0:15], v[52:55], v[148:151], v[0:15]
	ds_read_b128 v[48:51], v219 offset:49152
	ds_read_b128 v[52:55], v219 offset:57344
	s_waitcnt lgkmcnt(1)
	v_mfma_f32_32x32x16_bf16 v[16:31], v[48:51], v[144:147], v[16:31]
	v_lshlrev_b32_e32 v48, 7, v254
	v_lshlrev_b32_e32 v49, 3, v254
	v_add_u32_e32 v59, s35, v48
	v_bitop3_b32 v220, v178, v49, s0 bitop3:0x78
	v_add_u32_e32 v221, v59, v220
	v_and_b32_e32 v58, 0x70, v49
	v_bitop3_b32 v222, v178, v58, 32 bitop3:0x36
	s_waitcnt lgkmcnt(0)
	v_mfma_f32_32x32x16_bf16 v[0:15], v[52:55], v[144:147], v[0:15]
	ds_read_b128 v[50:53], v221
	ds_read_b128 v[54:57], v221 offset:4096
	v_add_u32_e32 v223, v59, v222
	v_bitop3_b32 v224, v178, v58, 64 bitop3:0x36
	v_add_u32_e32 v225, v59, v224
	v_bitop3_b32 v226, v178, v58, s76 bitop3:0x36
	v_add_u32_e32 v227, v59, v226
	s_waitcnt lgkmcnt(1)
	v_mfma_f32_32x32x16_bf16 v[16:31], v[50:53], v[140:143], v[16:31]
	s_waitcnt lgkmcnt(0)
	v_mfma_f32_32x32x16_bf16 v[0:15], v[54:57], v[140:143], v[0:15]
	ds_read_b128 v[50:53], v223
	ds_read_b128 v[54:57], v223 offset:4096
	s_waitcnt lgkmcnt(1)
	v_mfma_f32_32x32x16_bf16 v[16:31], v[50:53], v[136:139], v[16:31]
	s_waitcnt lgkmcnt(0)
	v_mfma_f32_32x32x16_bf16 v[0:15], v[54:57], v[136:139], v[0:15]
	ds_read_b128 v[50:53], v225
	ds_read_b128 v[54:57], v225 offset:4096
	s_waitcnt lgkmcnt(1)
	v_mfma_f32_32x32x16_bf16 v[16:31], v[50:53], v[132:135], v[16:31]
	s_waitcnt lgkmcnt(0)
	v_mfma_f32_32x32x16_bf16 v[0:15], v[54:57], v[132:135], v[0:15]
	ds_read_b128 v[50:53], v227
	ds_read_b128 v[54:57], v227 offset:4096
	s_waitcnt lgkmcnt(1)
	v_mfma_f32_32x32x16_bf16 v[16:31], v[50:53], v[128:131], v[16:31]
	s_waitcnt lgkmcnt(0)
	v_mfma_f32_32x32x16_bf16 v[0:15], v[54:57], v[128:131], v[0:15]
	s_nop 9
	v_max_f32_e32 v49, v16, v17
	v_max3_f32 v49, v49, v18, v19
	v_max3_f32 v49, v49, v20, v21
	v_max3_f32 v49, v49, v22, v23
	v_max3_f32 v49, v49, v24, v25
	v_max3_f32 v49, v49, v26, v27
	v_max3_f32 v49, v49, v28, v29
	v_max3_f32 v49, v49, v30, v31
	v_max3_f32 v49, v49, v0, v1
	v_max3_f32 v49, v49, v2, v3
	v_max3_f32 v49, v49, v4, v5
	v_max3_f32 v49, v49, v6, v7
	v_max3_f32 v49, v49, v8, v9
	v_max3_f32 v49, v49, v10, v11
	v_max3_f32 v49, v49, v12, v13
	v_max3_f32 v49, v49, v14, v15
	v_mov_b32_e32 v50, v49
	s_nop 1
	v_permlane32_swap_b32_e32 v49, v50
	v_max_f32_e32 v49, v49, v50
	v_add_f32_e32 v50, 0x7149f2ca, v49
	v_cmp_ge_f32_e32 vcc, s78, v50
	s_cmp_eq_u64 vcc, exec
	s_cselect_b64 s[0:1], -1, 0
	s_and_b64 vcc, exec, s[66:67]
	s_cbranch_vccz .LBB0_597
	s_waitcnt vmcnt(0) lgkmcnt(0)
	s_barrier
	s_mov_b64 s[4:5], 0

; #define SBAR() __builtin_amdgcn_sched_barrier(0)
; #define LW(n) asm volatile("s_waitcnt lgkmcnt(" #n ")" ::: "memory")
; template <int MODE, bool PF> __device__ __forceinline__ void pv_partial(f32x16* o, int vb, bf16x8 pa0, bf16x8 pa1, bf16x8 pa2, bf16x8 pa3, f32x16& p0, f32x16& p1, float& m_reg, float& alpha) {
;     VFrag fa, fb;
;     v_frag_read<0>(fa, vb);
;     if constexpr (PF) { v_frag_read<1>(fb, vb); LW(8); } else LW(0);
;     SBAR();
;     pv_mma(o[0], fa, pa0, pa1, pa2, pa3);
;     float pm0 = p0[0];
; #pragma unroll
;     for (int r = 1; r < 16; ++r) pm0 = fmaxf(pm0, p0[r]);
;     if constexpr (PF) { v_frag_read<2>(fa, vb); LW(8); } else { v_frag_read<1>(fb, vb); LW(0); }
;     SBAR();
;     pv_mma(o[1], fb, pa0, pa1, pa2, pa3);
;     float pmax = pm0;
; #pragma unroll
;     for (int r = 0; r < 16; ++r) pmax = fmaxf(pmax, p1[r]);
;     { auto rr = __builtin_amdgcn_permlane32_swap(__float_as_uint(pmax), __float_as_uint(pmax), false, false);
;       pmax = fmaxf(__uint_as_float(rr[0]), __uint_as_float(rr[1])); }
;     const float mn = (pmax - m_reg > Cst<MODE>::THRS) ? fmaxf(m_reg, pmax) : m_reg;
;     alpha = __builtin_amdgcn_exp2f(m_reg - mn); m_reg = mn;
;     const f32x16 mnv = {mn, mn, mn, mn, mn, mn, mn, mn, mn, mn, mn, mn, mn, mn, mn, mn};
;     if constexpr (PF) { v_frag_read<3>(fb, vb); LW(8); } else { v_frag_read<2>(fa, vb); LW(0); }
;     SBAR();
;     pv_mma(o[2], fa, pa0, pa1, pa2, pa3);
;     p0 = p0 - mnv; p1 = p1 - mnv;
; #pragma unroll
;     for (int r = 0; r < 8; ++r) p0[r] = __builtin_amdgcn_exp2f(p0[r]);
;     if constexpr (PF) { LW(0); } else { v_frag_read<3>(fb, vb); LW(0); }
;     SBAR();
;     pv_mma(o[3], fb, pa0, pa1, pa2, pa3);
; #pragma unroll
;     for (int r = 8; r < 16; ++r) p0[r] = __builtin_amdgcn_exp2f(p0[r]);
;     asm volatile("" : "+v"(p0), "+v"(p1));
; }
.LBB0_604:
	v_add_u32_e32 v197, s93, v203
	ds_read_b64_tr_b16 v[64:65], v197 offset:0
	ds_read_b64_tr_b16 v[66:67], v197 offset:0x800
	ds_read_b64_tr_b16 v[68:69], v197 offset:0x1000
	ds_read_b64_tr_b16 v[70:71], v197 offset:0x1800
	ds_read_b64_tr_b16 v[88:89], v197 offset:0x2000
	ds_read_b64_tr_b16 v[90:91], v197 offset:0x2800
	ds_read_b64_tr_b16 v[92:93], v197 offset:0x3000
	ds_read_b64_tr_b16 v[94:95], v197 offset:0x3800
	s_waitcnt lgkmcnt(0)
	s_nop 0
	v_mfma_f32_32x32x16_bf16 v[0:15], v[84:87], v[64:67], v[0:15]
	v_max_f32_e32 v64, v112, v113
	v_max3_f32 v64, v64, v114, v115
	v_max3_f32 v64, v64, v116, v117
	v_max3_f32 v64, v64, v118, v119
	v_max3_f32 v64, v64, v120, v121
	v_mfma_f32_32x32x16_bf16 v[0:15], v[72:75], v[68:71], v[0:15]
	v_max3_f32 v64, v64, v122, v123
	v_max3_f32 v64, v64, v124, v125
	v_max3_f32 v198, v64, v126, v127
	ds_read_b64_tr_b16 v[64:65], v197 offset:0x200
	ds_read_b64_tr_b16 v[66:67], v197 offset:0xa00
	ds_read_b64_tr_b16 v[68:69], v197 offset:0x1200
	ds_read_b64_tr_b16 v[70:71], v197 offset:0x1a00
	v_mfma_f32_32x32x16_bf16 v[0:15], v[76:79], v[88:91], v[0:15]
	ds_read_b64_tr_b16 v[88:89], v197 offset:0x2200
	ds_read_b64_tr_b16 v[90:91], v197 offset:0x2a00
	v_mfma_f32_32x32x16_bf16 v[0:15], v[80:83], v[92:95], v[0:15]
	ds_read_b64_tr_b16 v[92:93], v197 offset:0x3200
	ds_read_b64_tr_b16 v[94:95], v197 offset:0x3a00
	s_waitcnt lgkmcnt(0)
	v_mfma_f32_32x32x16_bf16 v[48:63], v[84:87], v[64:67], v[48:63]
	v_max3_f32 v64, v198, v96, v97
	v_max3_f32 v64, v64, v98, v99
	v_max3_f32 v64, v64, v100, v101
	v_max3_f32 v64, v64, v102, v103
	v_max3_f32 v64, v64, v104, v105
	v_max3_f32 v64, v64, v106, v107
	v_max3_f32 v64, v64, v108, v109
	v_mfma_f32_32x32x16_bf16 v[48:63], v[72:75], v[68:71], v[48:63]
	v_max3_f32 v64, v64, v110, v111
	v_mov_b32_e32 v65, v64
	s_nop 1
	v_permlane32_swap_b32_e32 v64, v65
	v_max_f32_e32 v64, v64, v65
	v_mfma_f32_32x32x16_bf16 v[48:63], v[76:79], v[88:91], v[48:63]
	v_sub_f32_e32 v65, v64, v243
	v_cmp_lt_f32_e32 vcc, s78, v65
	v_max_f32_e32 v65, v243, v243
	v_max_f32_e32 v64, v65, v64
	v_cndmask_b32_e32 v244, v243, v64, vcc
	v_sub_f32_e32 v64, v243, v244
	v_exp_f32_e32 v246, v64
	ds_read_b64_tr_b16 v[64:65], v197 offset:0x400
	ds_read_b64_tr_b16 v[66:67], v197 offset:0xc00
	ds_read_b64_tr_b16 v[68:69], v197 offset:0x1400
	v_mfma_f32_32x32x16_bf16 v[48:63], v[80:83], v[92:95], v[48:63]
	ds_read_b64_tr_b16 v[70:71], v197 offset:0x1c00
	ds_read_b64_tr_b16 v[88:89], v197 offset:0x2400
	ds_read_b64_tr_b16 v[90:91], v197 offset:0x2c00
	ds_read_b64_tr_b16 v[92:93], v197 offset:0x3400
	ds_read_b64_tr_b16 v[94:95], v197 offset:0x3c00
	s_waitcnt lgkmcnt(0)
	v_mfma_f32_32x32x16_bf16 v[32:47], v[84:87], v[64:67], v[32:47]
	v_sub_f32_e32 v65, v113, v244
	v_sub_f32_e32 v64, v112, v244
	v_sub_f32_e32 v113, v97, v244
	v_sub_f32_e32 v112, v96, v244
	v_sub_f32_e32 v67, v115, v244
	v_sub_f32_e32 v66, v114, v244
	v_sub_f32_e32 v115, v99, v244
	v_mfma_f32_32x32x16_bf16 v[32:47], v[72:75], v[68:71], v[32:47]
	v_sub_f32_e32 v114, v98, v244
	v_sub_f32_e32 v71, v119, v244
	v_sub_f32_e32 v70, v118, v244
	v_sub_f32_e32 v69, v117, v244
	v_sub_f32_e32 v68, v116, v244
	v_sub_f32_e32 v117, v101, v244
	v_sub_f32_e32 v116, v100, v244
	v_mfma_f32_32x32x16_bf16 v[32:47], v[76:79], v[88:91], v[32:47]
	ds_read_b64_tr_b16 v[88:89], v197 offset:0x600
	ds_read_b64_tr_b16 v[90:91], v197 offset:0xe00
	v_sub_f32_e32 v119, v103, v244
	v_sub_f32_e32 v118, v102, v244
	v_exp_f32_e32 v64, v64
	v_exp_f32_e32 v65, v65
	v_exp_f32_e32 v66, v66
	v_mfma_f32_32x32x16_bf16 v[32:47], v[80:83], v[92:95], v[32:47]
	ds_read_b64_tr_b16 v[92:93], v197 offset:0x1600
	ds_read_b64_tr_b16 v[94:95], v197 offset:0x1e00
	ds_read_b64_tr_b16 v[96:97], v197 offset:0x2600
	ds_read_b64_tr_b16 v[98:99], v197 offset:0x2e00
	ds_read_b64_tr_b16 v[100:101], v197 offset:0x3600
	v_exp_f32_e32 v67, v67
	v_exp_f32_e32 v68, v68
	v_exp_f32_e32 v69, v69
	v_exp_f32_e32 v70, v70
	v_exp_f32_e32 v71, v71
	ds_read_b64_tr_b16 v[102:103], v197 offset:0x3e00
	s_waitcnt lgkmcnt(0)
	v_sub_f32_e32 v198, v127, v244
	v_sub_f32_e32 v199, v126, v244
	v_sub_f32_e32 v200, v125, v244
	v_sub_f32_e32 v201, v124, v244
	v_sub_f32_e32 v243, v123, v244
	v_sub_f32_e32 v247, v122, v244
	v_sub_f32_e32 v248, v121, v244
	v_sub_f32_e32 v249, v120, v244
	v_sub_f32_e32 v127, v111, v244
	v_sub_f32_e32 v126, v110, v244
	v_sub_f32_e32 v125, v109, v244
	v_sub_f32_e32 v124, v108, v244
	v_sub_f32_e32 v123, v107, v244
	v_sub_f32_e32 v122, v106, v244
	v_sub_f32_e32 v121, v105, v244
	v_sub_f32_e32 v120, v104, v244
	v_mfma_f32_32x32x16_bf16 v[16:31], v[84:87], v[88:91], v[16:31]
	v_cmp_gt_f32_e32 vcc, 1.0, v246
	v_mfma_f32_32x32x16_bf16 v[16:31], v[72:75], v[92:95], v[16:31]
	v_exp_f32_e32 v72, v249
	v_exp_f32_e32 v73, v248
	v_exp_f32_e32 v74, v247
	v_exp_f32_e32 v75, v243
	v_mfma_f32_32x32x16_bf16 v[16:31], v[76:79], v[96:99], v[16:31]
	v_exp_f32_e32 v76, v201
	v_exp_f32_e32 v77, v200
	v_exp_f32_e32 v78, v199
	v_exp_f32_e32 v79, v198
	v_mfma_f32_32x32x16_bf16 v[16:31], v[80:83], v[100:103], v[16:31]
	s_cbranch_vccz .LBB0_608
	s_and_saveexec_b64 s[74:75], s[0:1]
	ds_write_b32 v179, v246 offset:128
	s_or_b64 exec, exec, s[74:75]
	s_waitcnt lgkmcnt(0)
	v_add_u32_e32 v92, s81, v178
	ds_read_b128 v[80:83], v92 offset:224
	ds_read_b128 v[84:87], v92 offset:192
	ds_read_b128 v[88:91], v92 offset:160
	ds_read_b128 v[92:95], v92 offset:128
	s_waitcnt lgkmcnt(0)
	v_pk_mul_f32 v[12:13], v[12:13], v[80:81]
	v_pk_mul_f32 v[8:9], v[8:9], v[84:85]
	v_pk_mul_f32 v[4:5], v[4:5], v[88:89]
	v_pk_mul_f32 v[14:15], v[14:15], v[82:83]
	v_pk_mul_f32 v[10:11], v[10:11], v[86:87]
	v_pk_mul_f32 v[6:7], v[6:7], v[90:91]
	v_pk_mul_f32 v[2:3], v[2:3], v[94:95]
	v_pk_mul_f32 v[0:1], v[0:1], v[92:93]
	v_pk_mul_f32 v[60:61], v[60:61], v[80:81]
	v_pk_mul_f32 v[56:57], v[56:57], v[84:85]
	v_pk_mul_f32 v[52:53], v[52:53], v[88:89]
	v_pk_mul_f32 v[62:63], v[62:63], v[82:83]
	v_pk_mul_f32 v[58:59], v[58:59], v[86:87]
	v_pk_mul_f32 v[54:55], v[54:55], v[90:91]
	v_pk_mul_f32 v[50:51], v[50:51], v[94:95]
	v_pk_mul_f32 v[48:49], v[48:49], v[92:93]
	v_pk_mul_f32 v[44:45], v[44:45], v[80:81]
	v_pk_mul_f32 v[40:41], v[40:41], v[84:85]
	v_pk_mul_f32 v[36:37], v[36:37], v[88:89]
	v_pk_mul_f32 v[46:47], v[46:47], v[82:83]
	v_pk_mul_f32 v[42:43], v[42:43], v[86:87]
	v_pk_mul_f32 v[38:39], v[38:39], v[90:91]
	v_pk_mul_f32 v[34:35], v[34:35], v[94:95]
	v_pk_mul_f32 v[32:33], v[32:33], v[92:93]
	v_pk_mul_f32 v[28:29], v[28:29], v[80:81]
	v_pk_mul_f32 v[24:25], v[24:25], v[84:85]
	v_pk_mul_f32 v[20:21], v[20:21], v[88:89]
	v_pk_mul_f32 v[30:31], v[30:31], v[82:83]
	v_pk_mul_f32 v[26:27], v[26:27], v[86:87]
	v_pk_mul_f32 v[22:23], v[22:23], v[90:91]
	v_pk_mul_f32 v[18:19], v[18:19], v[94:95]
	v_pk_mul_f32 v[16:17], v[16:17], v[92:93]

; #define SBAR() __builtin_amdgcn_sched_barrier(0)
; #define LW(n) asm volatile("s_waitcnt lgkmcnt(" #n ")" ::: "memory")
; template <int MODE, bool PF> __device__ __forceinline__ void pv_partial(f32x16* o, int vb, bf16x8 pa0, bf16x8 pa1, bf16x8 pa2, bf16x8 pa3, f32x16& p0, f32x16& p1, float& m_reg, float& alpha) {
;     VFrag fa, fb;
;     v_frag_read<0>(fa, vb);
;     if constexpr (PF) { v_frag_read<1>(fb, vb); LW(8); } else LW(0);
;     SBAR();
;     pv_mma(o[0], fa, pa0, pa1, pa2, pa3);
;     float pm0 = p0[0];
; #pragma unroll
;     for (int r = 1; r < 16; ++r) pm0 = fmaxf(pm0, p0[r]);
;     if constexpr (PF) { v_frag_read<2>(fa, vb); LW(8); } else { v_frag_read<1>(fb, vb); LW(0); }
;     SBAR();
;     pv_mma(o[1], fb, pa0, pa1, pa2, pa3);
;     float pmax = pm0;
; #pragma unroll
;     for (int r = 0; r < 16; ++r) pmax = fmaxf(pmax, p1[r]);
;     { auto rr = __builtin_amdgcn_permlane32_swap(__float_as_uint(pmax), __float_as_uint(pmax), false, false);
;       pmax = fmaxf(__uint_as_float(rr[0]), __uint_as_float(rr[1])); }
;     const float mn = (pmax - m_reg > Cst<MODE>::THRS) ? fmaxf(m_reg, pmax) : m_reg;
;     alpha = __builtin_amdgcn_exp2f(m_reg - mn); m_reg = mn;
;     const f32x16 mnv = {mn, mn, mn, mn, mn, mn, mn, mn, mn, mn, mn, mn, mn, mn, mn, mn};
;     if constexpr (PF) { v_frag_read<3>(fb, vb); LW(8); } else { v_frag_read<2>(fa, vb); LW(0); }
;     SBAR();
;     pv_mma(o[2], fa, pa0, pa1, pa2, pa3);
;     p0 = p0 - mnv; p1 = p1 - mnv;
; #pragma unroll
;     for (int r = 0; r < 8; ++r) p0[r] = __builtin_amdgcn_exp2f(p0[r]);
;     if constexpr (PF) { LW(0); } else { v_frag_read<3>(fb, vb); LW(0); }
;     SBAR();
;     pv_mma(o[3], fb, pa0, pa1, pa2, pa3);
; #pragma unroll
;     for (int r = 8; r < 16; ++r) p0[r] = __builtin_amdgcn_exp2f(p0[r]);
;     asm volatile("" : "+v"(p0), "+v"(p1));
; }
.LBB0_616:
	s_nop 0
	v_add_u32_e32 v126, s83, v203
	ds_read_b64_tr_b16 v[64:65], v126 offset:0
	ds_read_b64_tr_b16 v[66:67], v126 offset:0x800
	ds_read_b64_tr_b16 v[68:69], v126 offset:0x1000
	ds_read_b64_tr_b16 v[70:71], v126 offset:0x1800
	ds_read_b64_tr_b16 v[122:123], v126 offset:0x2000
	ds_read_b64_tr_b16 v[124:125], v126 offset:0x2800
	ds_read_b64_tr_b16 v[198:199], v126 offset:0x3000
	ds_read_b64_tr_b16 v[200:201], v126 offset:0x3800
	s_waitcnt lgkmcnt(0)
	s_nop 0
	v_mfma_f32_32x32x16_bf16 v[0:15], v[116:119], v[64:67], v[0:15]
	v_max_f32_e32 v64, v96, v97
	v_max3_f32 v64, v64, v98, v99
	v_max3_f32 v64, v64, v100, v101
	v_max3_f32 v64, v64, v102, v103
	v_max3_f32 v64, v64, v104, v105
	v_mfma_f32_32x32x16_bf16 v[0:15], v[72:75], v[68:71], v[0:15]
	v_max3_f32 v64, v64, v106, v107
	v_max3_f32 v64, v64, v108, v109
	v_max3_f32 v127, v64, v110, v111
	ds_read_b64_tr_b16 v[64:65], v126 offset:0x200
	ds_read_b64_tr_b16 v[66:67], v126 offset:0xa00
	ds_read_b64_tr_b16 v[68:69], v126 offset:0x1200
	ds_read_b64_tr_b16 v[70:71], v126 offset:0x1a00
	v_mfma_f32_32x32x16_bf16 v[0:15], v[76:79], v[122:125], v[0:15]
	ds_read_b64_tr_b16 v[122:123], v126 offset:0x2200
	ds_read_b64_tr_b16 v[124:125], v126 offset:0x2a00
	v_mfma_f32_32x32x16_bf16 v[0:15], v[112:115], v[198:201], v[0:15]
	ds_read_b64_tr_b16 v[198:199], v126 offset:0x3200
	ds_read_b64_tr_b16 v[200:201], v126 offset:0x3a00
	s_waitcnt lgkmcnt(0)
	v_mfma_f32_32x32x16_bf16 v[48:63], v[116:119], v[64:67], v[48:63]
	v_max3_f32 v64, v127, v80, v81
	v_max3_f32 v64, v64, v82, v83
	v_max3_f32 v64, v64, v84, v85
	v_max3_f32 v64, v64, v86, v87
	v_max3_f32 v64, v64, v88, v89
	v_max3_f32 v64, v64, v90, v91
	v_max3_f32 v64, v64, v92, v93
	v_mfma_f32_32x32x16_bf16 v[48:63], v[72:75], v[68:71], v[48:63]
	v_max3_f32 v64, v64, v94, v95
	v_mov_b32_e32 v65, v64
	s_nop 1
	v_permlane32_swap_b32_e32 v64, v65
	v_max_f32_e32 v64, v64, v65
	v_mfma_f32_32x32x16_bf16 v[48:63], v[76:79], v[122:125], v[48:63]
	v_sub_f32_e32 v65, v64, v244
	v_cmp_lt_f32_e32 vcc, s78, v65
	v_max_f32_e32 v65, v244, v244
	v_max_f32_e32 v64, v65, v64
	v_cndmask_b32_e32 v243, v244, v64, vcc
	v_sub_f32_e32 v64, v244, v243
	v_exp_f32_e32 v244, v64
	ds_read_b64_tr_b16 v[64:65], v126 offset:0x400
	ds_read_b64_tr_b16 v[66:67], v126 offset:0xc00
	ds_read_b64_tr_b16 v[68:69], v126 offset:0x1400
	v_mfma_f32_32x32x16_bf16 v[48:63], v[112:115], v[198:201], v[48:63]
	ds_read_b64_tr_b16 v[70:71], v126 offset:0x1c00
	ds_read_b64_tr_b16 v[122:123], v126 offset:0x2400
	ds_read_b64_tr_b16 v[124:125], v126 offset:0x2c00
	ds_read_b64_tr_b16 v[198:199], v126 offset:0x3400
	ds_read_b64_tr_b16 v[200:201], v126 offset:0x3c00
	s_waitcnt lgkmcnt(0)
	v_mfma_f32_32x32x16_bf16 v[32:47], v[116:119], v[64:67], v[32:47]
	v_sub_f32_e32 v65, v97, v243
	v_sub_f32_e32 v64, v96, v243
	ds_read_b64_tr_b16 v[96:97], v126 offset:0x600
	v_sub_f32_e32 v67, v99, v243
	v_sub_f32_e32 v66, v98, v243
	ds_read_b64_tr_b16 v[98:99], v126 offset:0xe00
	v_sub_f32_e32 v127, v107, v243
	v_mfma_f32_32x32x16_bf16 v[32:47], v[72:75], v[68:71], v[32:47]
	v_sub_f32_e32 v69, v101, v243
	v_sub_f32_e32 v68, v100, v243
	ds_read_b64_tr_b16 v[100:101], v126 offset:0x1600
	v_sub_f32_e32 v71, v103, v243
	v_sub_f32_e32 v70, v102, v243
	ds_read_b64_tr_b16 v[102:103], v126 offset:0x1e00
	v_exp_f32_e32 v64, v64
	v_mfma_f32_32x32x16_bf16 v[32:47], v[76:79], v[122:125], v[32:47]
	v_sub_f32_e32 v124, v109, v243
	v_sub_f32_e32 v125, v108, v243
	v_sub_f32_e32 v122, v111, v243
	v_sub_f32_e32 v123, v110, v243
	v_exp_f32_e32 v65, v65
	v_exp_f32_e32 v66, v66
	v_exp_f32_e32 v67, v67
	v_mfma_f32_32x32x16_bf16 v[32:47], v[112:115], v[198:201], v[32:47]
	v_sub_f32_e32 v199, v105, v243
	v_sub_f32_e32 v200, v104, v243
	ds_read_b64_tr_b16 v[104:105], v126 offset:0x2600
	v_sub_f32_e32 v198, v106, v243
	ds_read_b64_tr_b16 v[106:107], v126 offset:0x2e00
	ds_read_b64_tr_b16 v[108:109], v126 offset:0x3600
	v_exp_f32_e32 v68, v68
	v_exp_f32_e32 v69, v69
	v_exp_f32_e32 v70, v70
	v_exp_f32_e32 v71, v71
	ds_read_b64_tr_b16 v[110:111], v126 offset:0x3e00
	s_waitcnt lgkmcnt(0)
	v_sub_f32_e32 v95, v95, v243
	v_sub_f32_e32 v94, v94, v243
	v_sub_f32_e32 v93, v93, v243
	v_sub_f32_e32 v92, v92, v243
	v_sub_f32_e32 v91, v91, v243
	v_sub_f32_e32 v90, v90, v243
	v_sub_f32_e32 v89, v89, v243
	v_sub_f32_e32 v88, v88, v243
	v_sub_f32_e32 v87, v87, v243
	v_sub_f32_e32 v86, v86, v243
	v_sub_f32_e32 v85, v85, v243
	v_sub_f32_e32 v84, v84, v243
	v_sub_f32_e32 v83, v83, v243
	v_sub_f32_e32 v82, v82, v243
	v_sub_f32_e32 v81, v81, v243
	v_sub_f32_e32 v80, v80, v243
	v_mfma_f32_32x32x16_bf16 v[16:31], v[116:119], v[96:99], v[16:31]
	v_cmp_gt_f32_e32 vcc, 1.0, v244
	v_mfma_f32_32x32x16_bf16 v[16:31], v[72:75], v[100:103], v[16:31]
	v_exp_f32_e32 v72, v200
	v_exp_f32_e32 v73, v199
	v_exp_f32_e32 v74, v198
	v_exp_f32_e32 v75, v127
	v_mfma_f32_32x32x16_bf16 v[16:31], v[76:79], v[104:107], v[16:31]
	v_exp_f32_e32 v76, v125
	v_exp_f32_e32 v77, v124
	v_exp_f32_e32 v78, v123
	v_exp_f32_e32 v79, v122
	v_mfma_f32_32x32x16_bf16 v[16:31], v[112:115], v[108:111], v[16:31]
	s_cbranch_vccz .LBB0_620
	s_and_saveexec_b64 s[74:75], s[0:1]
	ds_write_b32 v179, v244 offset:128
	s_or_b64 exec, exec, s[74:75]
	s_waitcnt lgkmcnt(0)
	v_add_u32_e32 v108, s81, v178
	ds_read_b128 v[96:99], v108 offset:224
	ds_read_b128 v[100:103], v108 offset:192
	ds_read_b128 v[104:107], v108 offset:160
	ds_read_b128 v[108:111], v108 offset:128
	s_waitcnt lgkmcnt(0)
	v_pk_mul_f32 v[12:13], v[12:13], v[96:97]
	v_pk_mul_f32 v[8:9], v[8:9], v[100:101]
	v_pk_mul_f32 v[4:5], v[4:5], v[104:105]
	v_pk_mul_f32 v[14:15], v[14:15], v[98:99]
	v_pk_mul_f32 v[10:11], v[10:11], v[102:103]
	v_pk_mul_f32 v[6:7], v[6:7], v[106:107]
	v_pk_mul_f32 v[2:3], v[2:3], v[110:111]
	v_pk_mul_f32 v[0:1], v[0:1], v[108:109]
	v_pk_mul_f32 v[60:61], v[60:61], v[96:97]
	v_pk_mul_f32 v[56:57], v[56:57], v[100:101]
	v_pk_mul_f32 v[52:53], v[52:53], v[104:105]
	v_pk_mul_f32 v[62:63], v[62:63], v[98:99]
	v_pk_mul_f32 v[58:59], v[58:59], v[102:103]
	v_pk_mul_f32 v[54:55], v[54:55], v[106:107]
	v_pk_mul_f32 v[50:51], v[50:51], v[110:111]
	v_pk_mul_f32 v[48:49], v[48:49], v[108:109]
	v_pk_mul_f32 v[44:45], v[44:45], v[96:97]
	v_pk_mul_f32 v[40:41], v[40:41], v[100:101]
	v_pk_mul_f32 v[36:37], v[36:37], v[104:105]
	v_pk_mul_f32 v[46:47], v[46:47], v[98:99]
	v_pk_mul_f32 v[42:43], v[42:43], v[102:103]
	v_pk_mul_f32 v[38:39], v[38:39], v[106:107]
	v_pk_mul_f32 v[34:35], v[34:35], v[110:111]
	v_pk_mul_f32 v[32:33], v[32:33], v[108:109]
	v_pk_mul_f32 v[28:29], v[28:29], v[96:97]
	v_pk_mul_f32 v[24:25], v[24:25], v[100:101]
	v_pk_mul_f32 v[20:21], v[20:21], v[104:105]
	v_pk_mul_f32 v[30:31], v[30:31], v[98:99]
	v_pk_mul_f32 v[26:27], v[26:27], v[102:103]
	v_pk_mul_f32 v[22:23], v[22:23], v[106:107]
	v_pk_mul_f32 v[18:19], v[18:19], v[110:111]
	v_pk_mul_f32 v[16:17], v[16:17], v[108:109]

; #define SBAR() __builtin_amdgcn_sched_barrier(0)
; #define LW(n) asm volatile("s_waitcnt lgkmcnt(" #n ")" ::: "memory")
; template <int MODE, bool PF> __device__ __forceinline__ void pv_partial(f32x16* o, int vb, bf16x8 pa0, bf16x8 pa1, bf16x8 pa2, bf16x8 pa3, f32x16& p0, f32x16& p1, float& m_reg, float& alpha) {
;     VFrag fa, fb;
;     v_frag_read<0>(fa, vb);
;     if constexpr (PF) { v_frag_read<1>(fb, vb); LW(8); } else LW(0);
;     SBAR();
;     pv_mma(o[0], fa, pa0, pa1, pa2, pa3);
;     float pm0 = p0[0];
; #pragma unroll
;     for (int r = 1; r < 16; ++r) pm0 = fmaxf(pm0, p0[r]);
;     if constexpr (PF) { v_frag_read<2>(fa, vb); LW(8); } else { v_frag_read<1>(fb, vb); LW(0); }
;     SBAR();
;     pv_mma(o[1], fb, pa0, pa1, pa2, pa3);
;     float pmax = pm0;
; #pragma unroll
;     for (int r = 0; r < 16; ++r) pmax = fmaxf(pmax, p1[r]);
;     { auto rr = __builtin_amdgcn_permlane32_swap(__float_as_uint(pmax), __float_as_uint(pmax), false, false);
;       pmax = fmaxf(__uint_as_float(rr[0]), __uint_as_float(rr[1])); }
;     const float mn = (pmax - m_reg > Cst<MODE>::THRS) ? fmaxf(m_reg, pmax) : m_reg;
;     alpha = __builtin_amdgcn_exp2f(m_reg - mn); m_reg = mn;
;     const f32x16 mnv = {mn, mn, mn, mn, mn, mn, mn, mn, mn, mn, mn, mn, mn, mn, mn, mn};
;     if constexpr (PF) { v_frag_read<3>(fb, vb); LW(8); } else { v_frag_read<2>(fa, vb); LW(0); }
;     SBAR();
;     pv_mma(o[2], fa, pa0, pa1, pa2, pa3);
;     p0 = p0 - mnv; p1 = p1 - mnv;
; #pragma unroll
;     for (int r = 0; r < 8; ++r) p0[r] = __builtin_amdgcn_exp2f(p0[r]);
;     if constexpr (PF) { LW(0); } else { v_frag_read<3>(fb, vb); LW(0); }
;     SBAR();
;     pv_mma(o[3], fb, pa0, pa1, pa2, pa3);
; #pragma unroll
;     for (int r = 8; r < 16; ++r) p0[r] = __builtin_amdgcn_exp2f(p0[r]);
;     asm volatile("" : "+v"(p0), "+v"(p1));
; }
.LBB0_634:
	v_add_u32_e32 v129, s92, v203
	ds_read_b64_tr_b16 v[64:65], v129 offset:0
	ds_read_b64_tr_b16 v[66:67], v129 offset:0x800
	ds_read_b64_tr_b16 v[68:69], v129 offset:0x1000
	ds_read_b64_tr_b16 v[70:71], v129 offset:0x1800
	ds_read_b64_tr_b16 v[80:81], v129 offset:0x2000
	ds_read_b64_tr_b16 v[82:83], v129 offset:0x2800
	ds_read_b64_tr_b16 v[84:85], v129 offset:0x3000
	ds_read_b64_tr_b16 v[86:87], v129 offset:0x3800
	s_waitcnt lgkmcnt(0)
	s_nop 0
	v_mfma_f32_32x32x16_bf16 v[0:15], v[140:143], v[64:67], v[0:15]
	v_max_f32_e32 v64, v113, v113
	v_max_f32_e32 v65, v112, v112
	v_max_f32_e32 v64, v65, v64
	v_max3_f32 v64, v64, v114, v115
	v_max3_f32 v64, v64, v116, v117
	v_max3_f32 v64, v64, v118, v119
	v_max3_f32 v64, v64, v120, v121
	v_mfma_f32_32x32x16_bf16 v[0:15], v[72:75], v[68:71], v[0:15]
	v_max3_f32 v64, v64, v122, v123
	v_max3_f32 v66, v64, v124, v125
	ds_read_b64_tr_b16 v[64:65], v129 offset:0x200
	v_max3_f32 v92, v66, v126, v127
	ds_read_b64_tr_b16 v[66:67], v129 offset:0xa00
	ds_read_b64_tr_b16 v[68:69], v129 offset:0x1200
	ds_read_b64_tr_b16 v[70:71], v129 offset:0x1a00
	v_mfma_f32_32x32x16_bf16 v[0:15], v[76:79], v[80:83], v[0:15]
	ds_read_b64_tr_b16 v[80:81], v129 offset:0x2200
	ds_read_b64_tr_b16 v[82:83], v129 offset:0x2a00
	ds_read_b64_tr_b16 v[88:89], v129 offset:0x3200
	ds_read_b64_tr_b16 v[90:91], v129 offset:0x3a00
	s_waitcnt lgkmcnt(0)
	v_mfma_f32_32x32x16_bf16 v[0:15], v[132:135], v[84:87], v[0:15]
	v_mfma_f32_32x32x16_bf16 v[48:63], v[140:143], v[64:67], v[48:63]
	v_max3_f32 v84, v92, v96, v97
	v_max3_f32 v84, v84, v98, v99
	v_max3_f32 v84, v84, v100, v101
	v_max3_f32 v84, v84, v102, v103
	v_max3_f32 v84, v84, v104, v105
	v_max3_f32 v84, v84, v106, v107
	v_max3_f32 v64, v84, v108, v109
	v_mfma_f32_32x32x16_bf16 v[48:63], v[72:75], v[68:71], v[48:63]
	v_max3_f32 v64, v64, v110, v111
	v_mov_b32_e32 v65, v64
	s_nop 1
	v_permlane32_swap_b32_e32 v64, v65
	v_max_f32_e32 v64, v64, v65
	v_mfma_f32_32x32x16_bf16 v[48:63], v[76:79], v[80:83], v[48:63]
	v_sub_f32_e32 v65, v64, v243
	v_max_f32_e32 v66, v243, v243
	v_max_f32_e32 v64, v66, v64
	v_cmp_lt_f32_e32 vcc, s78, v65
	s_nop 1
	v_cndmask_b32_e32 v130, v243, v64, vcc
	v_sub_f32_e32 v64, v243, v130
	v_exp_f32_e32 v128, v64
	ds_read_b64_tr_b16 v[64:65], v129 offset:0x400
	ds_read_b64_tr_b16 v[66:67], v129 offset:0xc00
	ds_read_b64_tr_b16 v[68:69], v129 offset:0x1400
	ds_read_b64_tr_b16 v[70:71], v129 offset:0x1c00
	v_mfma_f32_32x32x16_bf16 v[48:63], v[132:135], v[88:91], v[48:63]
	ds_read_b64_tr_b16 v[80:81], v129 offset:0x2400
	ds_read_b64_tr_b16 v[82:83], v129 offset:0x2c00
	ds_read_b64_tr_b16 v[136:137], v129 offset:0x3400
	ds_read_b64_tr_b16 v[138:139], v129 offset:0x3c00
	s_waitcnt lgkmcnt(0)
	v_mfma_f32_32x32x16_bf16 v[32:47], v[140:143], v[64:67], v[32:47]
	v_sub_f32_e32 v85, v101, v130
	v_sub_f32_e32 v84, v100, v130
	v_sub_f32_e32 v87, v103, v130
	v_sub_f32_e32 v86, v102, v130
	v_sub_f32_e32 v89, v105, v130
	v_sub_f32_e32 v88, v104, v130
	v_sub_f32_e32 v91, v107, v130
	v_mfma_f32_32x32x16_bf16 v[32:47], v[72:75], v[68:71], v[32:47]
	v_sub_f32_e32 v90, v106, v130
	v_sub_f32_e32 v119, v119, v130
	v_sub_f32_e32 v118, v118, v130
	v_sub_f32_e32 v117, v117, v130
	v_sub_f32_e32 v116, v116, v130
	v_sub_f32_e32 v67, v115, v130
	v_sub_f32_e32 v66, v114, v130
	v_mfma_f32_32x32x16_bf16 v[32:47], v[76:79], v[80:83], v[32:47]
	v_sub_f32_e32 v81, v97, v130
	v_sub_f32_e32 v80, v96, v130
	ds_read_b64_tr_b16 v[96:97], v129 offset:0x600
	v_sub_f32_e32 v83, v99, v130
	v_sub_f32_e32 v82, v98, v130
	ds_read_b64_tr_b16 v[98:99], v129 offset:0xe00
	ds_read_b64_tr_b16 v[100:101], v129 offset:0x1600
	v_mfma_f32_32x32x16_bf16 v[32:47], v[132:135], v[136:139], v[32:47]
	ds_read_b64_tr_b16 v[102:103], v129 offset:0x1e00
	ds_read_b64_tr_b16 v[104:105], v129 offset:0x2600
	ds_read_b64_tr_b16 v[106:107], v129 offset:0x2e00
	v_sub_f32_e32 v65, v113, v130
	v_sub_f32_e32 v64, v112, v130
	v_sub_f32_e32 v93, v109, v130
	v_sub_f32_e32 v92, v108, v130
	ds_read_b64_tr_b16 v[108:109], v129 offset:0x3600
	v_sub_f32_e32 v95, v111, v130
	v_sub_f32_e32 v94, v110, v130
	v_exp_f32_e32 v64, v64
	v_exp_f32_e32 v65, v65
	v_exp_f32_e32 v66, v66
	v_exp_f32_e32 v67, v67
	v_exp_f32_e32 v68, v116
	v_exp_f32_e32 v69, v117
	v_exp_f32_e32 v70, v118
	v_exp_f32_e32 v71, v119
	ds_read_b64_tr_b16 v[110:111], v129 offset:0x3e00
	s_waitcnt lgkmcnt(0)
	v_sub_f32_e32 v127, v127, v130
	v_sub_f32_e32 v126, v126, v130
	v_sub_f32_e32 v125, v125, v130
	v_sub_f32_e32 v124, v124, v130
	v_sub_f32_e32 v123, v123, v130
	v_sub_f32_e32 v122, v122, v130
	v_sub_f32_e32 v121, v121, v130
	v_sub_f32_e32 v120, v120, v130
	v_mfma_f32_32x32x16_bf16 v[16:31], v[140:143], v[96:99], v[16:31]
	v_cmp_gt_f32_e32 vcc, 1.0, v128
	v_mfma_f32_32x32x16_bf16 v[16:31], v[72:75], v[100:103], v[16:31]
	v_exp_f32_e32 v72, v120
	v_exp_f32_e32 v73, v121
	v_exp_f32_e32 v74, v122
	v_exp_f32_e32 v75, v123
	v_mfma_f32_32x32x16_bf16 v[16:31], v[76:79], v[104:107], v[16:31]
	v_exp_f32_e32 v76, v124
	v_exp_f32_e32 v77, v125
	v_exp_f32_e32 v78, v126
	v_exp_f32_e32 v79, v127
	v_mfma_f32_32x32x16_bf16 v[16:31], v[132:135], v[108:111], v[16:31]
	s_cbranch_vccz .LBB0_638
	s_and_saveexec_b64 s[2:3], s[0:1]
	ds_write_b32 v179, v128 offset:128
	s_or_b64 exec, exec, s[2:3]
	s_waitcnt lgkmcnt(0)
	v_add_u32_e32 v108, s81, v178
	ds_read_b128 v[96:99], v108 offset:224
	ds_read_b128 v[100:103], v108 offset:192
	ds_read_b128 v[104:107], v108 offset:160
	ds_read_b128 v[108:111], v108 offset:128
	s_waitcnt lgkmcnt(0)
	v_pk_mul_f32 v[12:13], v[12:13], v[96:97]
	v_pk_mul_f32 v[8:9], v[8:9], v[100:101]
	v_pk_mul_f32 v[4:5], v[4:5], v[104:105]
	v_pk_mul_f32 v[14:15], v[14:15], v[98:99]
	v_pk_mul_f32 v[10:11], v[10:11], v[102:103]
	v_pk_mul_f32 v[6:7], v[6:7], v[106:107]
	v_pk_mul_f32 v[2:3], v[2:3], v[110:111]
	v_pk_mul_f32 v[0:1], v[0:1], v[108:109]
	v_pk_mul_f32 v[60:61], v[60:61], v[96:97]
	v_pk_mul_f32 v[56:57], v[56:57], v[100:101]
	v_pk_mul_f32 v[52:53], v[52:53], v[104:105]
	v_pk_mul_f32 v[62:63], v[62:63], v[98:99]
	v_pk_mul_f32 v[58:59], v[58:59], v[102:103]
	v_pk_mul_f32 v[54:55], v[54:55], v[106:107]
	v_pk_mul_f32 v[50:51], v[50:51], v[110:111]
	v_pk_mul_f32 v[48:49], v[48:49], v[108:109]
	v_pk_mul_f32 v[44:45], v[44:45], v[96:97]
	v_pk_mul_f32 v[40:41], v[40:41], v[100:101]
	v_pk_mul_f32 v[36:37], v[36:37], v[104:105]
	v_pk_mul_f32 v[46:47], v[46:47], v[98:99]
	v_pk_mul_f32 v[42:43], v[42:43], v[102:103]
	v_pk_mul_f32 v[38:39], v[38:39], v[106:107]
	v_pk_mul_f32 v[34:35], v[34:35], v[110:111]
	v_pk_mul_f32 v[32:33], v[32:33], v[108:109]
	v_pk_mul_f32 v[28:29], v[28:29], v[96:97]
	v_pk_mul_f32 v[24:25], v[24:25], v[100:101]
	v_pk_mul_f32 v[20:21], v[20:21], v[104:105]
	v_pk_mul_f32 v[30:31], v[30:31], v[98:99]
	v_pk_mul_f32 v[26:27], v[26:27], v[102:103]
	v_pk_mul_f32 v[22:23], v[22:23], v[106:107]
	v_pk_mul_f32 v[18:19], v[18:19], v[110:111]
	v_pk_mul_f32 v[16:17], v[16:17], v[108:109]
